# baseline (speedup 1.0000x reference)
; #define STAGE(Pp,BASE,br,kt) do{ const u16* _g=(BASE)+(size_t)(br)*K+(size_t)(kt)*64; \
;     _Pragma("unroll") for(int _i=0;_i<2;++_i){ unsigned _so=stoff[_i]; asm volatile("" : "+v"(_so)); \
;       __builtin_amdgcn_global_load_lds((const unsigned*)(_g+_so), (unsigned*)((char*)(Pp)+tid*16+_i*8192),16,0,0);} }while(0)
; template <int EPI, bool SPLIT>
; __device__ __forceinline__ void gemm_phase(const Params& P, const u16* __restrict__ A, const u16* __restrict__ Bt, int NT  , int K,
;                                            const float* xres, float* yout, char* lds) {
;     ...
;     if (EPI == EPI_UQ) {
;       if (tid < 256) {
;         const f32x4* sp = (const f32x4*)(P_sqpart + (size_t)(brow + tid) * 32);
;         float sq = 0.f;
; #pragma unroll
;         for (int i = 0; i < 8; ++i) { const f32x4 a = sp[i]; sq += (a[0] + a[1]) + (a[2] + a[3]); }
;         rstd_l[tid] = rsqrtf(sq * (1.f / 1024.f) + 1e-6f);
;       }
;     }
;     ...
;     STAGE(SBm(0,0),Bt,bcol,0); STAGE(SA(0,0),A,brow,0);
;     STAGE(SBm(0,1),Bt,bcol+128,0); STAGE(SA(0,1),A,brow+128,0);
.LBB0_391:
	s_lshl_b32 s18, s2, 8
	s_and_saveexec_b64 s[42:43], s[4:5]
	s_cbranch_execz .LBB0_393
	v_add_u32_e32 v164, s18, v130
	v_ashrrev_i32_e32 v165, 31, v164
	v_lshlrev_b64 v[164:165], 7, v[164:165]
	v_lshl_add_u64 v[194:195], s[12:13], 0, v[164:165]
	global_load_dwordx4 v[164:167], v[194:195], off
	global_load_dwordx4 v[168:171], v[194:195], off offset:16
	global_load_dwordx4 v[172:175], v[194:195], off offset:32
	global_load_dwordx4 v[176:179], v[194:195], off offset:48
	global_load_dwordx4 v[180:183], v[194:195], off offset:64
	global_load_dwordx4 v[186:189], v[194:195], off offset:80
	global_load_dwordx4 v[190:193], v[194:195], off offset:96
	s_nop 0
	global_load_dwordx4 v[194:197], v[194:195], off offset:112
.LBB0_393:
	s_or_b64 exec, exec, s[42:43]
	s_ashr_i32 s69, s68, 5
	s_lshl_b32 s0, s69, 8
	s_ashr_i32 s1, s0, 31
	s_lshl_b64 s[44:45], s[0:1], 11
	s_add_u32 s50, s10, s44
	v_mov_b32_e32 v128, v132
	v_add_u32_e32 v144, s56, v131
	s_addc_u32 s51, s11, s45
	v_readfirstlane_b32 s1, v144
	v_lshl_add_u64 v[0:1], v[128:129], 1, s[50:51]
	s_mov_b32 m0, s1
	v_mov_b32_e32 v128, v133
	v_add_u32_e32 v145, 0x2000, v144
	s_lshl_b64 s[46:47], s[18:19], 11
	global_load_lds_dwordx4 v[0:1], off
	v_readfirstlane_b32 s1, v145
	s_add_u32 s52, s64, s46
	v_add_u32_e32 v146, 16, v131
	v_lshl_add_u64 v[0:1], v[128:129], 1, s[50:51]
	s_mov_b32 m0, s1
	s_addc_u32 s53, s65, s47
	v_mov_b32_e32 v128, v132
	v_readfirstlane_b32 s1, v146
	v_add_u32_e32 v147, 0x2000, v146
	global_load_lds_dwordx4 v[0:1], off
	s_mov_b32 m0, s1
	v_lshl_add_u64 v[0:1], v[128:129], 1, s[52:53]
	v_readfirstlane_b32 s1, v147
	s_bitset1_b32 s0, 7
	global_load_lds_dwordx4 v[0:1], off
	v_mov_b32_e32 v128, v133
	s_mov_b32 m0, s1
	s_ashr_i32 s1, s0, 31
	s_lshl_b64 s[0:1], s[0:1], 11
	v_lshl_add_u64 v[0:1], v[128:129], 1, s[52:53]
	s_add_u32 s54, s10, s0
	v_mov_b32_e32 v128, v132
	v_add_u32_e32 v148, s58, v131
	global_load_lds_dwordx4 v[0:1], off
	s_addc_u32 s55, s11, s1
	v_readfirstlane_b32 s0, v148
	v_add_u32_e32 v149, 0x2000, v148
	v_lshl_add_u64 v[0:1], v[128:129], 1, s[54:55]
	s_mov_b32 m0, s0
	v_mov_b32_e32 v128, v133
	v_readfirstlane_b32 s0, v149
	s_or_b32 s42, s18, 0x80
	s_mov_b32 s43, s19
	global_load_lds_dwordx4 v[0:1], off
	s_mov_b32 m0, s0
	s_lshl_b64 s[0:1], s[42:43], 11
	v_lshl_add_u64 v[0:1], v[128:129], 1, s[54:55]
	s_add_u32 s48, s64, s0
	v_mov_b32_e32 v128, v132
	v_add_u32_e32 v150, 0x4000, v146
	global_load_lds_dwordx4 v[0:1], off
	s_addc_u32 s49, s65, s1
	v_readfirstlane_b32 s0, v150
	v_add_u32_e32 v151, 0x6000, v146
	v_lshl_add_u64 v[0:1], v[128:129], 1, s[48:49]
	s_mov_b32 m0, s0
	v_mov_b32_e32 v128, v133
	v_readfirstlane_b32 s0, v151
	global_load_lds_dwordx4 v[0:1], off
	s_mov_b32 m0, s0
	v_lshl_add_u64 v[0:1], v[128:129], 1, s[48:49]
	global_load_lds_dwordx4 v[0:1], off
	s_and_saveexec_b64 s[100:101], s[4:5]
	s_cbranch_execz .Lmy_rstd_skip
	s_waitcnt vmcnt(8)
	s_mov_b32 s0, 0x800000
	v_mov_b32_e32 v198, v164
	v_mov_b32_e32 v199, v168
	v_mov_b32_e32 v168, v165
	v_mov_b32_e32 v164, v166
	v_mov_b32_e32 v165, v170
	v_mov_b32_e32 v170, v167
	v_mov_b32_e32 v166, v173
	v_mov_b32_e32 v167, v174
	v_mov_b32_e32 v173, v175
	v_pk_add_f32 v[168:169], v[198:199], v[168:169]
	v_pk_add_f32 v[164:165], v[164:165], v[170:171]
	v_pk_add_f32 v[166:167], v[166:167], v[172:173]
	v_pk_add_f32 v[164:165], v[168:169], v[164:165]
	v_pk_add_f32 v[166:167], v[166:167], v[166:167] op_sel:[0,1] op_sel_hi:[1,0]
	v_add_f32_e32 v164, 0, v164
	v_add_f32_e32 v174, v176, v177
	v_add_f32_e32 v176, v178, v179
	v_mov_b32_e32 v179, v180
	v_mov_b32_e32 v175, v182
	v_mov_b32_e32 v177, v183
	v_mov_b32_e32 v167, v181
	v_add_f32_e32 v178, v164, v165
	v_mov_b32_e32 v182, v187
	v_mov_b32_e32 v183, v188
	v_mov_b32_e32 v187, v189
	v_pk_add_f32 v[170:171], v[174:175], v[176:177]
	v_pk_add_f32 v[164:165], v[178:179], v[166:167]
	v_pk_add_f32 v[172:173], v[182:183], v[186:187]
	v_pk_add_f32 v[164:165], v[164:165], v[170:171]
	v_pk_add_f32 v[168:169], v[172:173], v[172:173] op_sel:[0,1] op_sel_hi:[1,0]
	v_pk_add_f32 v[164:165], v[164:165], v[164:165] op_sel:[0,1] op_sel_hi:[1,0]
	v_add_f32_e32 v188, v190, v191
	v_add_f32_e32 v190, v192, v193
	v_mov_b32_e32 v189, v196
	v_mov_b32_e32 v191, v197
	v_mov_b32_e32 v169, v195
	v_mov_b32_e32 v165, v194
	v_pk_add_f32 v[174:175], v[188:189], v[190:191]
	v_pk_add_f32 v[164:165], v[164:165], v[168:169]
	s_nop 0
	v_pk_add_f32 v[164:165], v[164:165], v[174:175]
	s_nop 0
	v_add_f32_e32 v164, v164, v165
	v_fmamk_f32 v164, v164, 0x3a800000, v138
	v_mul_f32_e32 v165, 0x4b800000, v164
	v_cmp_gt_f32_e32 vcc, s0, v164
	s_nop 1
	v_cndmask_b32_e32 v164, v164, v165, vcc
	v_rsq_f32_e32 v164, v164
	s_nop 0
	v_mul_f32_e32 v165, 0x45800000, v164
	v_cndmask_b32_e32 v164, v164, v165, vcc
	ds_write_b32 v136, v164
.Lmy_rstd_skip:
	s_or_b64 exec, exec, s[100:101]
	s_andn2_b64 vcc, exec, s[14:15]
	s_cbranch_vccnz .LBB0_395
	s_barrier
